# CONV loop: bias and four tap-weight quads (row independent) loaded once before the loop; four round trips per item instead of eight
# baseline (speedup 1.0000x reference)
.LBB0_1231:
	s_andn2_b64 vcc, exec, s[0:1]
	s_cbranch_vccnz .LBB0_1289
	s_cmp_gt_i32 s79, 9
	s_mov_b64 s[0:1], -1
	s_cbranch_scc0 .LBB0_1237
	v_mov_b32_e32 v0, s63
	ds_read_b32 v0, v0
	s_add_i32 s2, s91, 0x20050
	s_waitcnt lgkmcnt(0)
	v_readfirstlane_b32 s0, v0
	v_mov_b32_e32 v0, s89
	ds_read_b32 v0, v0
	s_waitcnt lgkmcnt(0)
	v_readfirstlane_b32 s1, v0
	v_mov_b32_e32 v0, s2
	ds_read_b32 v0, v0
	s_add_i32 s2, s91, 0x20054
	s_waitcnt lgkmcnt(0)
	v_readfirstlane_b32 s4, v0
	v_mov_b32_e32 v0, s2
	ds_read_b32 v0, v0
	s_add_i32 s2, s91, 0x20058
	s_waitcnt lgkmcnt(0)
	v_readfirstlane_b32 s5, v0
	v_mov_b32_e32 v0, s2
	ds_read_b32 v0, v0
	s_add_i32 s2, s91, 0x2005c
	s_waitcnt lgkmcnt(0)
	v_readfirstlane_b32 s6, v0
	v_mov_b32_e32 v0, s2
	ds_read_b32 v0, v0
	s_mov_b32 s2, 0x420000
	v_cmp_gt_i32_e32 vcc, s2, v160
	s_waitcnt lgkmcnt(0)
	v_readfirstlane_b32 s7, v0
	s_and_saveexec_b64 s[2:3], vcc
	s_cbranch_execz .LBB0_1236
	v_readlane_b32 s9, v254, 26
	s_lshl_b32 s8, s9, 12
	s_lshl_b32 s9, s9, 14
	s_add_u32 s4, s4, s9
	s_addc_u32 s5, s5, 0
	s_add_u32 s6, s6, s8
	s_addc_u32 s7, s7, 0
	s_add_u32 s8, s0, 0x4200000
	s_addc_u32 s9, s1, 0
	s_add_u32 s10, s0, 0x8400000
	s_addc_u32 s11, s1, 0
	s_mov_b64 s[12:13], 0
	v_mov_b32_e32 v12, v160
	v_lshlrev_b32_e32 v62, 2, v160
	v_and_b32_e32 v62, 0x3fc, v62
	v_lshlrev_b32_e32 v62, 2, v62
	v_add_u32_e32 v63, 0x1000, v62
	v_add_u32_e32 v84, 0x2000, v62
	v_add_u32_e32 v85, 0x3000, v62
	global_load_dwordx4 v[64:67], v62, s[6:7]
	global_load_dwordx4 v[68:71], v62, s[4:5]
	global_load_dwordx4 v[72:75], v63, s[4:5]
	global_load_dwordx4 v[76:79], v84, s[4:5]
	global_load_dwordx4 v[80:83], v85, s[4:5]
.LBB0_1235:
	v_ashrrev_i32_e32 v0, 8, v12
	v_cmp_gt_i32_e32 vcc, s92, v0
	v_mov_b32_e32 v2, 0x7fffff00
	v_mov_b32_e32 v3, 0xffffe000
	v_lshlrev_b32_e32 v1, 2, v12
	v_cndmask_b32_e32 v2, v2, v3, vcc
	v_cndmask_b32_e32 v3, v227, v238, vcc
	v_and_b32_e32 v1, 0x3fc, v1
	v_and_b32_e32 v28, v3, v0
	v_cndmask_b32_e32 v13, v155, v253, vcc
	v_and_b32_e32 v25, v2, v0
	v_lshlrev_b32_e32 v152, 2, v1
	v_lshlrev_b32_e32 v2, 1, v1
	v_add_u32_e32 v1, -2, v28
	v_cmp_lt_u32_e32 vcc, 1, v28
	v_cmp_lt_u32_e64 s[0:1], v1, v13
	s_and_b64 vcc, vcc, s[0:1]
	v_cndmask_b32_e32 v1, v28, v1, vcc
	v_add_u32_e32 v14, v1, v25
	v_mov_b32_e32 v3, v153
	v_ashrrev_i32_e32 v15, 31, v14
	v_lshl_add_u64 v[6:7], s[8:9], 0, v[2:3]
	v_lshlrev_b64 v[14:15], 11, v[14:15]
	v_lshl_add_u64 v[14:15], v[6:7], 0, v[14:15]
	global_load_dwordx2 v[14:15], v[14:15], off
	v_add_u32_e32 v1, -1, v28
	v_cndmask_b32_e64 v22, 0, 1.0, vcc
	v_cmp_lt_u32_e32 vcc, v1, v13
	v_lshl_add_u64 v[4:5], s[4:5], 0, v[152:153]
	v_add_u32_e32 v1, 1, v28
	v_cndmask_b32_e64 v24, 0, 1.0, vcc
	v_add_u32_e32 v12, s24, v12
	s_waitcnt vmcnt(0)
	v_lshlrev_b32_e32 v18, 16, v14
	v_and_b32_e32 v19, 0xffff0000, v14
	v_lshlrev_b32_e32 v20, 16, v15
	v_and_b32_e32 v21, 0xffff0000, v15
	v_pk_mul_f32 v[14:15], v[68:69], v[18:19]
	v_add_u32_e32 v18, v25, v28
	v_pk_fma_f32 v[14:15], v[14:15], v[22:23], v[64:65] op_sel_hi:[1,0,1]
	v_subbrev_co_u32_e64 v8, s[0:1], 0, v18, vcc
	v_ashrrev_i32_e32 v9, 31, v8
	v_lshlrev_b64 v[8:9], 11, v[8:9]
	v_lshl_add_u64 v[8:9], v[6:7], 0, v[8:9]
	global_load_dwordx2 v[8:9], v[8:9], off
	v_add_co_u32_e32 v26, vcc, s65, v4
	v_pk_mul_f32 v[16:17], v[70:71], v[20:21]
	s_nop 0
	v_addc_co_u32_e32 v27, vcc, 0, v5, vcc
	v_pk_fma_f32 v[16:17], v[16:17], v[22:23], v[66:67] op_sel_hi:[1,0,1]
	v_ashrrev_i32_e32 v19, 31, v18
	v_cmp_lt_u32_e32 vcc, v28, v13
	s_waitcnt vmcnt(0)
	v_lshlrev_b32_e32 v20, 16, v8
	v_and_b32_e32 v21, 0xffff0000, v8
	v_lshlrev_b32_e32 v22, 16, v9
	v_and_b32_e32 v23, 0xffff0000, v9
	v_pk_mul_f32 v[8:9], v[72:73], v[20:21]
	s_nop 0
	v_pk_fma_f32 v[14:15], v[24:25], v[8:9], v[14:15] op_sel_hi:[0,1,1]
	v_lshlrev_b64 v[8:9], 11, v[18:19]
	v_lshl_add_u64 v[8:9], v[6:7], 0, v[8:9]
	global_load_dwordx2 v[8:9], v[8:9], off
	v_pk_mul_f32 v[10:11], v[74:75], v[22:23]
	v_cndmask_b32_e64 v22, 0, 1.0, vcc
	v_pk_fma_f32 v[16:17], v[24:25], v[10:11], v[16:17] op_sel_hi:[0,1,1]
	v_cmp_lt_u32_e32 vcc, v1, v13
	s_waitcnt vmcnt(0)
	v_lshlrev_b32_e32 v18, 16, v8
	v_and_b32_e32 v19, 0xffff0000, v8
	v_lshlrev_b32_e32 v20, 16, v9
	v_and_b32_e32 v21, 0xffff0000, v9
	v_cndmask_b32_e32 v1, v28, v1, vcc
	v_pk_mul_f32 v[8:9], v[76:77], v[18:19]
	s_nop 0
	v_pk_fma_f32 v[8:9], v[22:23], v[8:9], v[14:15] op_sel_hi:[0,1,1]
	v_add_u32_e32 v14, v1, v25
	v_ashrrev_i32_e32 v15, 31, v14
	v_lshlrev_b64 v[14:15], 11, v[14:15]
	v_lshl_add_u64 v[6:7], v[6:7], 0, v[14:15]
	global_load_dwordx2 v[6:7], v[6:7], off
	v_cndmask_b32_e64 v18, 0, 1.0, vcc
	v_add_co_u32_e32 v4, vcc, s85, v4
	v_pk_mul_f32 v[10:11], v[78:79], v[20:21]
	s_nop 0
	v_addc_co_u32_e32 v5, vcc, 0, v5, vcc
	v_pk_fma_f32 v[10:11], v[22:23], v[10:11], v[16:17] op_sel_hi:[0,1,1]
	v_ashrrev_i32_e32 v1, 31, v0
	v_lshlrev_b64 v[0:1], 11, v[0:1]
	v_lshl_add_u64 v[0:1], s[10:11], 0, v[0:1]
	v_cmp_lt_i32_e32 vcc, s46, v12
	v_lshl_add_u64 v[0:1], v[0:1], 0, v[2:3]
	s_or_b64 s[12:13], vcc, s[12:13]
	s_waitcnt vmcnt(0)
	v_lshlrev_b32_e32 v14, 16, v6
	v_and_b32_e32 v15, 0xffff0000, v6
	v_lshlrev_b32_e32 v16, 16, v7
	v_and_b32_e32 v17, 0xffff0000, v7
	v_pk_mul_f32 v[4:5], v[80:81], v[14:15]
	v_pk_mul_f32 v[6:7], v[82:83], v[16:17]
	v_pk_fma_f32 v[4:5], v[18:19], v[4:5], v[8:9] op_sel_hi:[0,1,1]
	v_pk_fma_f32 v[6:7], v[18:19], v[6:7], v[10:11] op_sel_hi:[0,1,1]
	v_cvt_pk_bf16_f32 v2, v4, v5
	v_cvt_pk_bf16_f32 v3, v6, v7
	global_store_dwordx2 v[0:1], v[2:3], off
	s_andn2_b64 exec, exec, s[12:13]
	s_cbranch_execnz .LBB0_1235
